# nt streaming hint on row-phase X/Y loads (7 row loops, 52 loads)
# speedup vs baseline: 1.0089x; 1.0089x over previous
; DI unsigned pk2(float lo, float hi) { f32x2 v = {lo, hi}; bf16x2_t b = __builtin_convertvector(v, bf16x2_t); return __builtin_bit_cast(unsigned, b); }
; DI float bflo(unsigned u) { return __uint_as_float(u << 16); }
; DI float bfhi(unsigned u) { return __uint_as_float(u & 0xffff0000u); }
; DI void st16_wt(void* p, u32x4 v) { asm volatile("global_store_dwordx4 %0, %1, off sc0 sc1\n\ts_nop 1" :: "v"(p), "v"(v) : "memory"); }
; DI void row_phase(int wv, int mode, const float* X, const bf16_t* Y, const float* ga, float coef, const float* gb, float* Xout, bf16_t* A, int a_pad) {
;     ...
;     for (int r = gw; r < MTOK; r += NGW) {
;         f32x4 v[4];
; #pragma unroll
;         for (int j = 0; j < 4; ++j) v[j] = *(const f32x4*)(X + (size_t)r * DM + 4 * lane + 256 * j);
;         if (mode == 1) { f32x4 y[4]; float s = 0.f;
; #pragma unroll
;             for (int j = 0; j < 4; ++j) { const u32x2 yv = *(const u32x2*)(Y + (size_t)r * DM + 4 * lane + 256 * j); y[j] = (f32x4){bflo(yv.x), bfhi(yv.x), bflo(yv.y), bfhi(yv.y)}; s += y[j][0] * y[j][0] + y[j][1] * y[j][1] + y[j][2] * y[j][2] + y[j][3] * y[j][3]; }
;             const float rs = coef * rsqrtf(wave_sum(s) * (1.f / DM) + 1e-6f);
; #pragma unroll
;             for (int j = 0; j < 4; ++j) { const f32x4 gg = *(const f32x4*)(ga + 4 * lane + 256 * j); v[j] += y[j] * gg * rs; } }
;         if (Xout) {
; #pragma unroll
;             for (int j = 0; j < 4; ++j) st16_wt(Xout + (size_t)r * DM + 4 * lane + 256 * j, __builtin_bit_cast(u32x4, v[j])); }
;         if (gb) { float s = 0.f;
; #pragma unroll
;             for (int j = 0; j < 4; ++j) s += v[j][0] * v[j][0] + v[j][1] * v[j][1] + v[j][2] * v[j][2] + v[j][3] * v[j][3];
;             const float rs = rsqrtf(wave_sum(s) * (1.f / DM) + 1e-6f);
;             const size_t ar = a_pad ? (size_t)(r + (r >> 13) + 1) : (size_t)r;
; #pragma unroll
;             for (int j = 0; j < 4; ++j) { const f32x4 gg = *(const f32x4*)(gb + 4 * lane + 256 * j); const f32x4 o = v[j] * gg * rs;
;                 u32x2 w; w.x = pk2(o[0], o[1]); w.y = pk2(o[2], o[3]); *(u32x2*)(A + ar * DM + 4 * lane + 256 * j) = w; } }
.LBB0_321:
	s_and_b64 vcc, exec, s[2:3]
	s_cbranch_vccnz .LBB0_320
	global_load_dwordx4 v[8:11], v[6:7], off offset:-3072 nt
	global_load_dwordx4 v[12:15], v[6:7], off offset:-2048 nt
	global_load_dwordx4 v[16:19], v[6:7], off offset:-1024 nt
	global_load_dwordx4 v[20:23], v[6:7], off nt
	global_load_dwordx4 v[24:27], v[0:1], off
	global_load_dwordx4 v[96:99], v[0:1], off offset:1024
	global_load_dwordx4 v[100:103], v[0:1], off offset:2048
	global_load_dwordx4 v[104:107], v[0:1], off offset:3072
	s_waitcnt vmcnt(0)
	v_mul_f32_e32 v28, v9, v9
	v_mul_f32_e32 v29, v13, v13
	v_mul_f32_e32 v30, v17, v17
	v_fmac_f32_e32 v28, v8, v8
	v_fmac_f32_e32 v29, v12, v12
	v_mul_f32_e32 v31, v21, v21
	v_fmac_f32_e32 v30, v16, v16
	v_fmac_f32_e32 v28, v10, v10
	v_fmac_f32_e32 v29, v14, v14
	v_fmac_f32_e32 v31, v20, v20
	v_fmac_f32_e32 v30, v18, v18
	v_fmac_f32_e32 v28, v11, v11
	v_fmac_f32_e32 v29, v15, v15
	v_fmac_f32_e32 v31, v22, v22
	v_fmac_f32_e32 v30, v19, v19
	v_add_f32_e32 v28, v28, v29
	v_fmac_f32_e32 v31, v23, v23
	v_add_f32_e32 v28, v28, v30
	v_add_f32_e32 v28, v28, v31
	v_pk_mul_f32 v[8:9], v[8:9], v[24:25]
	v_pk_mul_f32 v[10:11], v[10:11], v[26:27]
	v_add_f32_dpp v28, v28, v28 quad_perm:[1,0,3,2] row_mask:0xf bank_mask:0xf bound_ctrl:1
	s_nop 1
	v_add_f32_dpp v28, v28, v28 quad_perm:[2,3,0,1] row_mask:0xf bank_mask:0xf bound_ctrl:1
	s_nop 1
	v_add_f32_dpp v28, v28, v28 row_half_mirror row_mask:0xf bank_mask:0xf bound_ctrl:1
	s_nop 1
	v_add_f32_dpp v28, v28, v28 row_mirror row_mask:0xf bank_mask:0xf bound_ctrl:1
	v_mov_b32_e32 v29, v28
	s_nop 1
	v_permlane16_swap_b32_e32 v28, v29
	v_add_f32_e32 v28, v28, v29
	v_mov_b32_e32 v29, v28
	s_nop 1
	v_permlane32_swap_b32_e32 v28, v29
	v_add_f32_e32 v28, v28, v29
	v_fmamk_f32 v28, v28, 0x3a800000, v3
	v_mul_f32_e32 v29, 0x4b800000, v28
	v_cmp_gt_f32_e32 vcc, s11, v28
	s_nop 1
	v_cndmask_b32_e32 v28, v28, v29, vcc
	v_rsq_f32_e32 v28, v28
	s_nop 0
	v_mul_f32_e32 v24, 0x45800000, v28
	v_cndmask_b32_e32 v24, v28, v24, vcc
	v_pk_mul_f32 v[10:11], v[10:11], v[24:25] op_sel_hi:[1,0]
	v_pk_mul_f32 v[8:9], v[8:9], v[24:25] op_sel_hi:[1,0]
	s_nop 0
	v_cvt_pk_bf16_f32 v8, v8, v9
	v_cvt_pk_bf16_f32 v9, v10, v11
	flat_store_dwordx2 v[4:5], v[8:9]
	v_pk_mul_f32 v[10:11], v[14:15], v[98:99]
	v_pk_mul_f32 v[8:9], v[12:13], v[96:97]
	v_pk_mul_f32 v[10:11], v[10:11], v[24:25] op_sel_hi:[1,0]
	v_pk_mul_f32 v[8:9], v[8:9], v[24:25] op_sel_hi:[1,0]
	s_nop 0
	v_cvt_pk_bf16_f32 v8, v8, v9
	v_cvt_pk_bf16_f32 v9, v10, v11
	flat_store_dwordx2 v[4:5], v[8:9] offset:512
	v_pk_mul_f32 v[10:11], v[18:19], v[102:103]
	v_pk_mul_f32 v[8:9], v[16:17], v[100:101]
	v_pk_mul_f32 v[10:11], v[10:11], v[24:25] op_sel_hi:[1,0]
	v_pk_mul_f32 v[8:9], v[8:9], v[24:25] op_sel_hi:[1,0]
	s_nop 0
	v_cvt_pk_bf16_f32 v8, v8, v9
	v_cvt_pk_bf16_f32 v9, v10, v11
	flat_store_dwordx2 v[4:5], v[8:9] offset:1024
	v_pk_mul_f32 v[10:11], v[22:23], v[106:107]
	v_pk_mul_f32 v[8:9], v[20:21], v[104:105]
	v_pk_mul_f32 v[10:11], v[10:11], v[24:25] op_sel_hi:[1,0]
	v_pk_mul_f32 v[8:9], v[8:9], v[24:25] op_sel_hi:[1,0]
	s_nop 0
	v_cvt_pk_bf16_f32 v8, v8, v9
	v_cvt_pk_bf16_f32 v9, v10, v11
	flat_store_dwordx2 v[4:5], v[8:9] offset:1536
	s_branch .LBB0_320

; DI unsigned pk2(float lo, float hi) { f32x2 v = {lo, hi}; bf16x2_t b = __builtin_convertvector(v, bf16x2_t); return __builtin_bit_cast(unsigned, b); }
; DI float bflo(unsigned u) { return __uint_as_float(u << 16); }
; DI float bfhi(unsigned u) { return __uint_as_float(u & 0xffff0000u); }
; DI void st16_wt(void* p, u32x4 v) { asm volatile("global_store_dwordx4 %0, %1, off sc0 sc1\n\ts_nop 1" :: "v"(p), "v"(v) : "memory"); }
; DI void row_phase(int wv, int mode, const float* X, const bf16_t* Y, const float* ga, float coef, const float* gb, float* Xout, bf16_t* A, int a_pad) {
;     ...
;     for (int r = gw; r < MTOK; r += NGW) {
;         f32x4 v[4];
; #pragma unroll
;         for (int j = 0; j < 4; ++j) v[j] = *(const f32x4*)(X + (size_t)r * DM + 4 * lane + 256 * j);
;         if (mode == 1) { f32x4 y[4]; float s = 0.f;
; #pragma unroll
;             for (int j = 0; j < 4; ++j) { const u32x2 yv = *(const u32x2*)(Y + (size_t)r * DM + 4 * lane + 256 * j); y[j] = (f32x4){bflo(yv.x), bfhi(yv.x), bflo(yv.y), bfhi(yv.y)}; s += y[j][0] * y[j][0] + y[j][1] * y[j][1] + y[j][2] * y[j][2] + y[j][3] * y[j][3]; }
;             const float rs = coef * rsqrtf(wave_sum(s) * (1.f / DM) + 1e-6f);
; #pragma unroll
;             for (int j = 0; j < 4; ++j) { const f32x4 gg = *(const f32x4*)(ga + 4 * lane + 256 * j); v[j] += y[j] * gg * rs; } }
;         if (Xout) {
; #pragma unroll
;             for (int j = 0; j < 4; ++j) st16_wt(Xout + (size_t)r * DM + 4 * lane + 256 * j, __builtin_bit_cast(u32x4, v[j])); }
;         if (gb) { float s = 0.f;
; #pragma unroll
;             for (int j = 0; j < 4; ++j) s += v[j][0] * v[j][0] + v[j][1] * v[j][1] + v[j][2] * v[j][2] + v[j][3] * v[j][3];
;             const float rs = rsqrtf(wave_sum(s) * (1.f / DM) + 1e-6f);
;             const size_t ar = a_pad ? (size_t)(r + (r >> 13) + 1) : (size_t)r;
; #pragma unroll
;             for (int j = 0; j < 4; ++j) { const f32x4 gg = *(const f32x4*)(gb + 4 * lane + 256 * j); const f32x4 o = v[j] * gg * rs;
;                 u32x2 w; w.x = pk2(o[0], o[1]); w.y = pk2(o[2], o[3]); *(u32x2*)(A + ar * DM + 4 * lane + 256 * j) = w; } }
.LBB0_521:
	v_lshl_add_u64 v[0:1], v[26:27], 0, v[18:19]
	v_add_co_u32_e32 v0, vcc, 0xa800000, v0
	v_lshl_add_u64 v[42:43], s[8:9], 0, v[28:29]
	s_nop 0
	v_addc_co_u32_e32 v1, vcc, 0, v1, vcc
	flat_load_dwordx2 v[46:47], v[0:1]
	flat_load_dwordx2 v[48:49], v[0:1] offset:512
	flat_load_dwordx2 v[50:51], v[0:1] offset:1024
	flat_load_dwordx2 v[52:53], v[0:1] offset:1536
	s_nop 0
	global_load_dwordx4 v[0:3], v[20:21], off nt
	global_load_dwordx4 v[4:7], v[20:21], off offset:1024 nt
	global_load_dwordx4 v[8:11], v[20:21], off offset:2048 nt
	global_load_dwordx4 v[12:15], v[20:21], off offset:3072 nt
	global_load_dwordx4 v[30:33], v[42:43], off nt
	global_load_dwordx4 v[34:37], v[42:43], off offset:1024 nt
	global_load_dwordx4 v[38:41], v[42:43], off offset:2048 nt
	s_nop 0
	global_load_dwordx4 v[42:45], v[42:43], off offset:3072 nt
	s_and_b64 vcc, exec, s[2:3]
	s_waitcnt vmcnt(0) lgkmcnt(0)
	v_and_b32_e32 v55, 0xffff0000, v46
	v_and_b32_e32 v57, 0xffff0000, v48
	v_lshlrev_b32_e32 v54, 16, v46
	v_lshlrev_b32_e32 v56, 16, v48
	v_and_b32_e32 v59, 0xffff0000, v50
	v_mul_f32_e32 v64, v55, v55
	v_mul_f32_e32 v65, v57, v57
	v_lshlrev_b32_e32 v46, 16, v47
	v_lshlrev_b32_e32 v48, 16, v49
	v_lshlrev_b32_e32 v58, 16, v50
	v_and_b32_e32 v61, 0xffff0000, v52
	v_mul_f32_e32 v66, v59, v59
	v_fmac_f32_e32 v64, v54, v54
	v_fmac_f32_e32 v65, v56, v56
	v_and_b32_e32 v47, 0xffff0000, v47
	v_and_b32_e32 v49, 0xffff0000, v49
	v_lshlrev_b32_e32 v50, 16, v51
	v_lshlrev_b32_e32 v60, 16, v52
	v_mul_f32_e32 v67, v61, v61
	v_fmac_f32_e32 v66, v58, v58
	v_fmac_f32_e32 v64, v46, v46
	v_fmac_f32_e32 v65, v48, v48
	v_and_b32_e32 v51, 0xffff0000, v51
	v_lshlrev_b32_e32 v52, 16, v53
	v_fmac_f32_e32 v67, v60, v60
	v_fmac_f32_e32 v66, v50, v50
	v_fmac_f32_e32 v64, v47, v47
	v_fmac_f32_e32 v65, v49, v49
	v_and_b32_e32 v53, 0xffff0000, v53
	v_pk_mul_f32 v[62:63], v[58:59], v[8:9]
	v_fmac_f32_e32 v67, v52, v52
	v_fmac_f32_e32 v66, v51, v51
	v_add_f32_e32 v8, v64, v65
	v_fmac_f32_e32 v67, v53, v53
	v_add_f32_e32 v8, v8, v66
	v_add_f32_e32 v8, v8, v67
	v_pk_mul_f32 v[0:1], v[54:55], v[0:1]
	v_pk_mul_f32 v[2:3], v[46:47], v[2:3]
	v_add_f32_dpp v8, v8, v8 quad_perm:[1,0,3,2] row_mask:0xf bank_mask:0xf bound_ctrl:1
	v_pk_mul_f32 v[4:5], v[56:57], v[4:5]
	v_pk_mul_f32 v[6:7], v[48:49], v[6:7]
	v_add_f32_dpp v8, v8, v8 quad_perm:[2,3,0,1] row_mask:0xf bank_mask:0xf bound_ctrl:1
	v_pk_mul_f32 v[46:47], v[50:51], v[10:11]
	v_pk_mul_f32 v[48:49], v[60:61], v[12:13]
	v_add_f32_dpp v8, v8, v8 row_half_mirror row_mask:0xf bank_mask:0xf bound_ctrl:1
	v_pk_mul_f32 v[50:51], v[52:53], v[14:15]
	s_nop 0
	v_add_f32_dpp v8, v8, v8 row_mirror row_mask:0xf bank_mask:0xf bound_ctrl:1
	v_mov_b32_e32 v9, v8
	s_nop 1
	v_permlane16_swap_b32_e32 v8, v9
	v_add_f32_e32 v8, v8, v9
	v_mov_b32_e32 v9, v8
	s_nop 1
	v_permlane32_swap_b32_e32 v8, v9
	v_add_f32_e32 v8, v8, v9
	v_fmamk_f32 v8, v8, 0x3a800000, v17
	v_mul_f32_e32 v9, 0x4b800000, v8
	v_cmp_gt_f32_e64 s[4:5], s22, v8
	s_nop 1
	v_cndmask_b32_e64 v8, v8, v9, s[4:5]
	v_rsq_f32_e32 v8, v8
	s_nop 0
	v_mul_f32_e32 v9, 0x45800000, v8
	v_cndmask_b32_e64 v8, v8, v9, s[4:5]
	v_mul_f32_e32 v52, 0.5, v8
	v_pk_fma_f32 v[14:15], v[2:3], v[52:53], v[32:33] op_sel_hi:[1,0,1]
	v_pk_fma_f32 v[12:13], v[0:1], v[52:53], v[30:31] op_sel_hi:[1,0,1]
	v_pk_fma_f32 v[10:11], v[6:7], v[52:53], v[36:37] op_sel_hi:[1,0,1]
	v_pk_fma_f32 v[8:9], v[4:5], v[52:53], v[34:35] op_sel_hi:[1,0,1]
	v_pk_fma_f32 v[6:7], v[46:47], v[52:53], v[40:41] op_sel_hi:[1,0,1]
	v_pk_fma_f32 v[4:5], v[62:63], v[52:53], v[38:39] op_sel_hi:[1,0,1]
	v_pk_fma_f32 v[2:3], v[50:51], v[52:53], v[44:45] op_sel_hi:[1,0,1]
	v_pk_fma_f32 v[0:1], v[48:49], v[52:53], v[42:43] op_sel_hi:[1,0,1]
	global_load_dwordx4 v[40:43], v[22:23], off
	global_load_dwordx4 v[44:47], v[22:23], off offset:1024
	global_load_dwordx4 v[48:51], v[22:23], off offset:2048
	global_load_dwordx4 v[52:55], v[22:23], off offset:3072
	s_cbranch_vccnz .LBB0_520
	s_load_dwordx4 s[28:31], s[0:1], 0x140
	s_waitcnt lgkmcnt(0)
	v_lshl_add_u64 v[30:31], s[28:29], 0, v[28:29]
	global_store_dwordx4 v[30:31], v[12:15], off sc0 sc1
	s_nop 1
	v_lshl_add_u64 v[32:33], v[30:31], 0, s[16:17]
	global_store_dwordx4 v[32:33], v[8:11], off sc0 sc1
	s_nop 1
	v_lshl_add_u64 v[34:35], v[30:31], 0, s[18:19]
	global_store_dwordx4 v[34:35], v[4:7], off sc0 sc1
	s_nop 1
	v_lshl_add_u64 v[36:37], v[30:31], 0, s[20:21]
	global_store_dwordx4 v[36:37], v[0:3], off sc0 sc1
	s_nop 1
	s_branch .LBB0_520

; DI unsigned pk2(float lo, float hi) { f32x2 v = {lo, hi}; bf16x2_t b = __builtin_convertvector(v, bf16x2_t); return __builtin_bit_cast(unsigned, b); }
; DI float bflo(unsigned u) { return __uint_as_float(u << 16); }
; DI float bfhi(unsigned u) { return __uint_as_float(u & 0xffff0000u); }
; DI void st16_wt(void* p, u32x4 v) { asm volatile("global_store_dwordx4 %0, %1, off sc0 sc1\n\ts_nop 1" :: "v"(p), "v"(v) : "memory"); }
; DI void row_phase(int wv, int mode, const float* X, const bf16_t* Y, const float* ga, float coef, const float* gb, float* Xout, bf16_t* A, int a_pad) {
;     ...
;     for (int r = gw; r < MTOK; r += NGW) {
;         f32x4 v[4];
; #pragma unroll
;         for (int j = 0; j < 4; ++j) v[j] = *(const f32x4*)(X + (size_t)r * DM + 4 * lane + 256 * j);
;         if (mode == 1) { f32x4 y[4]; float s = 0.f;
; #pragma unroll
;             for (int j = 0; j < 4; ++j) { const u32x2 yv = *(const u32x2*)(Y + (size_t)r * DM + 4 * lane + 256 * j); y[j] = (f32x4){bflo(yv.x), bfhi(yv.x), bflo(yv.y), bfhi(yv.y)}; s += y[j][0] * y[j][0] + y[j][1] * y[j][1] + y[j][2] * y[j][2] + y[j][3] * y[j][3]; }
;             const float rs = coef * rsqrtf(wave_sum(s) * (1.f / DM) + 1e-6f);
; #pragma unroll
;             for (int j = 0; j < 4; ++j) { const f32x4 gg = *(const f32x4*)(ga + 4 * lane + 256 * j); v[j] += y[j] * gg * rs; } }
;         if (Xout) {
; #pragma unroll
;             for (int j = 0; j < 4; ++j) st16_wt(Xout + (size_t)r * DM + 4 * lane + 256 * j, __builtin_bit_cast(u32x4, v[j])); }
;         if (gb) { float s = 0.f;
; #pragma unroll
;             for (int j = 0; j < 4; ++j) s += v[j][0] * v[j][0] + v[j][1] * v[j][1] + v[j][2] * v[j][2] + v[j][3] * v[j][3];
;             const float rs = rsqrtf(wave_sum(s) * (1.f / DM) + 1e-6f);
;             const size_t ar = a_pad ? (size_t)(r + (r >> 13) + 1) : (size_t)r;
; #pragma unroll
;             for (int j = 0; j < 4; ++j) { const f32x4 gg = *(const f32x4*)(gb + 4 * lane + 256 * j); const f32x4 o = v[j] * gg * rs;
;                 u32x2 w; w.x = pk2(o[0], o[1]); w.y = pk2(o[2], o[3]); *(u32x2*)(A + ar * DM + 4 * lane + 256 * j) = w; } }
.LBB0_1832:
	v_lshl_add_u64 v[0:1], v[26:27], 0, v[18:19]
	v_add_co_u32_e32 v0, vcc, 0x5000000, v0
	s_nop 1
	v_addc_co_u32_e32 v1, vcc, 0, v1, vcc
	flat_load_dwordx2 v[46:47], v[0:1]
	flat_load_dwordx2 v[48:49], v[0:1] offset:512
	flat_load_dwordx2 v[50:51], v[0:1] offset:1024
	flat_load_dwordx2 v[52:53], v[0:1] offset:1536
	s_nop 0
	global_load_dwordx4 v[0:3], v[20:21], off nt
	global_load_dwordx4 v[4:7], v[20:21], off offset:1024 nt
	global_load_dwordx4 v[8:11], v[20:21], off offset:2048 nt
	global_load_dwordx4 v[12:15], v[20:21], off offset:3072 nt
	global_load_dwordx4 v[30:33], v[28:29], off nt
	global_load_dwordx4 v[34:37], v[28:29], off offset:1024 nt
	global_load_dwordx4 v[38:41], v[28:29], off offset:2048 nt
	global_load_dwordx4 v[42:45], v[28:29], off offset:3072 nt
	s_and_b64 vcc, exec, s[2:3]
	s_waitcnt vmcnt(0) lgkmcnt(0)
	v_and_b32_e32 v55, 0xffff0000, v46
	v_and_b32_e32 v57, 0xffff0000, v48
	v_lshlrev_b32_e32 v54, 16, v46
	v_lshlrev_b32_e32 v56, 16, v48
	v_and_b32_e32 v59, 0xffff0000, v50
	v_mul_f32_e32 v64, v55, v55
	v_mul_f32_e32 v65, v57, v57
	v_lshlrev_b32_e32 v46, 16, v47
	v_lshlrev_b32_e32 v48, 16, v49
	v_lshlrev_b32_e32 v58, 16, v50
	v_and_b32_e32 v61, 0xffff0000, v52
	v_mul_f32_e32 v66, v59, v59
	v_fmac_f32_e32 v64, v54, v54
	v_fmac_f32_e32 v65, v56, v56
	v_and_b32_e32 v47, 0xffff0000, v47
	v_and_b32_e32 v49, 0xffff0000, v49
	v_lshlrev_b32_e32 v50, 16, v51
	v_lshlrev_b32_e32 v60, 16, v52
	v_mul_f32_e32 v67, v61, v61
	v_fmac_f32_e32 v66, v58, v58
	v_fmac_f32_e32 v64, v46, v46
	v_fmac_f32_e32 v65, v48, v48
	v_and_b32_e32 v51, 0xffff0000, v51
	v_lshlrev_b32_e32 v52, 16, v53
	v_fmac_f32_e32 v67, v60, v60
	v_fmac_f32_e32 v66, v50, v50
	v_fmac_f32_e32 v64, v47, v47
	v_fmac_f32_e32 v65, v49, v49
	v_and_b32_e32 v53, 0xffff0000, v53
	v_pk_mul_f32 v[62:63], v[58:59], v[8:9]
	v_fmac_f32_e32 v67, v52, v52
	v_fmac_f32_e32 v66, v51, v51
	v_add_f32_e32 v8, v64, v65
	v_fmac_f32_e32 v67, v53, v53
	v_add_f32_e32 v8, v8, v66
	v_add_f32_e32 v8, v8, v67
	v_pk_mul_f32 v[0:1], v[54:55], v[0:1]
	v_pk_mul_f32 v[2:3], v[46:47], v[2:3]
	v_add_f32_dpp v8, v8, v8 quad_perm:[1,0,3,2] row_mask:0xf bank_mask:0xf bound_ctrl:1
	v_pk_mul_f32 v[4:5], v[56:57], v[4:5]
	v_pk_mul_f32 v[6:7], v[48:49], v[6:7]
	v_add_f32_dpp v8, v8, v8 quad_perm:[2,3,0,1] row_mask:0xf bank_mask:0xf bound_ctrl:1
	v_pk_mul_f32 v[46:47], v[50:51], v[10:11]
	v_pk_mul_f32 v[48:49], v[60:61], v[12:13]
	v_add_f32_dpp v8, v8, v8 row_half_mirror row_mask:0xf bank_mask:0xf bound_ctrl:1
	v_pk_mul_f32 v[50:51], v[52:53], v[14:15]
	s_nop 0
	v_add_f32_dpp v8, v8, v8 row_mirror row_mask:0xf bank_mask:0xf bound_ctrl:1
	v_mov_b32_e32 v9, v8
	s_nop 1
	v_permlane16_swap_b32_e32 v8, v9
	v_add_f32_e32 v8, v8, v9
	v_mov_b32_e32 v9, v8
	s_nop 1
	v_permlane32_swap_b32_e32 v8, v9
	v_add_f32_e32 v8, v8, v9
	v_fmamk_f32 v8, v8, 0x3a800000, v17
	v_mul_f32_e32 v9, 0x4b800000, v8
	v_cmp_gt_f32_e64 s[4:5], s20, v8
	s_nop 1
	v_cndmask_b32_e64 v8, v8, v9, s[4:5]
	v_rsq_f32_e32 v8, v8
	s_nop 0
	v_mul_f32_e32 v9, 0x45800000, v8
	v_cndmask_b32_e64 v52, v8, v9, s[4:5]
	v_pk_fma_f32 v[14:15], v[2:3], v[52:53], v[32:33] op_sel_hi:[1,0,1]
	v_pk_fma_f32 v[12:13], v[0:1], v[52:53], v[30:31] op_sel_hi:[1,0,1]
	v_pk_fma_f32 v[10:11], v[6:7], v[52:53], v[36:37] op_sel_hi:[1,0,1]
	v_pk_fma_f32 v[8:9], v[4:5], v[52:53], v[34:35] op_sel_hi:[1,0,1]
	v_pk_fma_f32 v[6:7], v[46:47], v[52:53], v[40:41] op_sel_hi:[1,0,1]
	v_pk_fma_f32 v[4:5], v[62:63], v[52:53], v[38:39] op_sel_hi:[1,0,1]
	v_pk_fma_f32 v[2:3], v[50:51], v[52:53], v[44:45] op_sel_hi:[1,0,1]
	v_pk_fma_f32 v[0:1], v[48:49], v[52:53], v[42:43] op_sel_hi:[1,0,1]
	global_load_dwordx4 v[40:43], v[22:23], off
	global_load_dwordx4 v[44:47], v[22:23], off offset:1024
	global_load_dwordx4 v[48:51], v[22:23], off offset:2048
	global_load_dwordx4 v[52:55], v[22:23], off offset:3072
	s_cbranch_vccnz .LBB0_1831
	global_store_dwordx4 v[28:29], v[12:15], off sc0 sc1
	s_nop 1
	v_lshl_add_u64 v[30:31], v[28:29], 0, s[14:15]
	global_store_dwordx4 v[30:31], v[8:11], off sc0 sc1
	s_nop 1
	v_lshl_add_u64 v[32:33], v[28:29], 0, s[16:17]
	global_store_dwordx4 v[32:33], v[4:7], off sc0 sc1
	s_nop 1
	v_lshl_add_u64 v[34:35], v[28:29], 0, s[18:19]
	global_store_dwordx4 v[34:35], v[0:3], off sc0 sc1
	s_nop 1
	s_branch .LBB0_1831

; DI unsigned pk2(float lo, float hi) { f32x2 v = {lo, hi}; bf16x2_t b = __builtin_convertvector(v, bf16x2_t); return __builtin_bit_cast(unsigned, b); }
; DI float bflo(unsigned u) { return __uint_as_float(u << 16); }
; DI float bfhi(unsigned u) { return __uint_as_float(u & 0xffff0000u); }
; DI void st16_wt(void* p, u32x4 v) { asm volatile("global_store_dwordx4 %0, %1, off sc0 sc1\n\ts_nop 1" :: "v"(p), "v"(v) : "memory"); }
; DI void row_phase(int wv, int mode, const float* X, const bf16_t* Y, const float* ga, float coef, const float* gb, float* Xout, bf16_t* A, int a_pad) {
;     ...
;     for (int r = gw; r < MTOK; r += NGW) {
;         f32x4 v[4];
; #pragma unroll
;         for (int j = 0; j < 4; ++j) v[j] = *(const f32x4*)(X + (size_t)r * DM + 4 * lane + 256 * j);
;         if (mode == 1) { f32x4 y[4]; float s = 0.f;
; #pragma unroll
;             for (int j = 0; j < 4; ++j) { const u32x2 yv = *(const u32x2*)(Y + (size_t)r * DM + 4 * lane + 256 * j); y[j] = (f32x4){bflo(yv.x), bfhi(yv.x), bflo(yv.y), bfhi(yv.y)}; s += y[j][0] * y[j][0] + y[j][1] * y[j][1] + y[j][2] * y[j][2] + y[j][3] * y[j][3]; }
;             const float rs = coef * rsqrtf(wave_sum(s) * (1.f / DM) + 1e-6f);
; #pragma unroll
;             for (int j = 0; j < 4; ++j) { const f32x4 gg = *(const f32x4*)(ga + 4 * lane + 256 * j); v[j] += y[j] * gg * rs; } }
;         if (Xout) {
; #pragma unroll
;             for (int j = 0; j < 4; ++j) st16_wt(Xout + (size_t)r * DM + 4 * lane + 256 * j, __builtin_bit_cast(u32x4, v[j])); }
;         if (gb) { float s = 0.f;
; #pragma unroll
;             for (int j = 0; j < 4; ++j) s += v[j][0] * v[j][0] + v[j][1] * v[j][1] + v[j][2] * v[j][2] + v[j][3] * v[j][3];
;             const float rs = rsqrtf(wave_sum(s) * (1.f / DM) + 1e-6f);
;             const size_t ar = a_pad ? (size_t)(r + (r >> 13) + 1) : (size_t)r;
; #pragma unroll
;             for (int j = 0; j < 4; ++j) { const f32x4 gg = *(const f32x4*)(gb + 4 * lane + 256 * j); const f32x4 o = v[j] * gg * rs;
;                 u32x2 w; w.x = pk2(o[0], o[1]); w.y = pk2(o[2], o[3]); *(u32x2*)(A + ar * DM + 4 * lane + 256 * j) = w; } }
.LBB0_2032:
	v_lshl_add_u64 v[0:1], v[26:27], 0, v[18:19]
	v_add_co_u32_e32 v0, vcc, 0xa800000, v0
	s_nop 1
	v_addc_co_u32_e32 v1, vcc, 0, v1, vcc
	flat_load_dwordx2 v[46:47], v[0:1]
	flat_load_dwordx2 v[48:49], v[0:1] offset:512
	flat_load_dwordx2 v[50:51], v[0:1] offset:1024
	flat_load_dwordx2 v[52:53], v[0:1] offset:1536
	s_nop 0
	global_load_dwordx4 v[0:3], v[20:21], off nt
	global_load_dwordx4 v[4:7], v[20:21], off offset:1024 nt
	global_load_dwordx4 v[8:11], v[20:21], off offset:2048 nt
	global_load_dwordx4 v[12:15], v[20:21], off offset:3072 nt
	global_load_dwordx4 v[30:33], v[28:29], off nt
	global_load_dwordx4 v[34:37], v[28:29], off offset:1024 nt
	global_load_dwordx4 v[38:41], v[28:29], off offset:2048 nt
	global_load_dwordx4 v[42:45], v[28:29], off offset:3072 nt
	s_and_b64 vcc, exec, s[2:3]
	s_waitcnt vmcnt(0) lgkmcnt(0)
	v_and_b32_e32 v55, 0xffff0000, v46
	v_and_b32_e32 v57, 0xffff0000, v48
	v_lshlrev_b32_e32 v54, 16, v46
	v_lshlrev_b32_e32 v56, 16, v48
	v_and_b32_e32 v59, 0xffff0000, v50
	v_mul_f32_e32 v64, v55, v55
	v_mul_f32_e32 v65, v57, v57
	v_lshlrev_b32_e32 v46, 16, v47
	v_lshlrev_b32_e32 v48, 16, v49
	v_lshlrev_b32_e32 v58, 16, v50
	v_and_b32_e32 v61, 0xffff0000, v52
	v_mul_f32_e32 v66, v59, v59
	v_fmac_f32_e32 v64, v54, v54
	v_fmac_f32_e32 v65, v56, v56
	v_and_b32_e32 v47, 0xffff0000, v47
	v_and_b32_e32 v49, 0xffff0000, v49
	v_lshlrev_b32_e32 v50, 16, v51
	v_lshlrev_b32_e32 v60, 16, v52
	v_mul_f32_e32 v67, v61, v61
	v_fmac_f32_e32 v66, v58, v58
	v_fmac_f32_e32 v64, v46, v46
	v_fmac_f32_e32 v65, v48, v48
	v_and_b32_e32 v51, 0xffff0000, v51
	v_lshlrev_b32_e32 v52, 16, v53
	v_fmac_f32_e32 v67, v60, v60
	v_fmac_f32_e32 v66, v50, v50
	v_fmac_f32_e32 v64, v47, v47
	v_fmac_f32_e32 v65, v49, v49
	v_and_b32_e32 v53, 0xffff0000, v53
	v_pk_mul_f32 v[62:63], v[58:59], v[8:9]
	v_fmac_f32_e32 v67, v52, v52
	v_fmac_f32_e32 v66, v51, v51
	v_add_f32_e32 v8, v64, v65
	v_fmac_f32_e32 v67, v53, v53
	v_add_f32_e32 v8, v8, v66
	v_add_f32_e32 v8, v8, v67
	v_pk_mul_f32 v[0:1], v[54:55], v[0:1]
	v_pk_mul_f32 v[2:3], v[46:47], v[2:3]
	v_add_f32_dpp v8, v8, v8 quad_perm:[1,0,3,2] row_mask:0xf bank_mask:0xf bound_ctrl:1
	v_pk_mul_f32 v[4:5], v[56:57], v[4:5]
	v_pk_mul_f32 v[6:7], v[48:49], v[6:7]
	v_add_f32_dpp v8, v8, v8 quad_perm:[2,3,0,1] row_mask:0xf bank_mask:0xf bound_ctrl:1
	v_pk_mul_f32 v[46:47], v[50:51], v[10:11]
	v_pk_mul_f32 v[48:49], v[60:61], v[12:13]
	v_add_f32_dpp v8, v8, v8 row_half_mirror row_mask:0xf bank_mask:0xf bound_ctrl:1
	v_pk_mul_f32 v[50:51], v[52:53], v[14:15]
	s_nop 0
	v_add_f32_dpp v8, v8, v8 row_mirror row_mask:0xf bank_mask:0xf bound_ctrl:1
	v_mov_b32_e32 v9, v8
	s_nop 1
	v_permlane16_swap_b32_e32 v8, v9
	v_add_f32_e32 v8, v8, v9
	v_mov_b32_e32 v9, v8
	s_nop 1
	v_permlane32_swap_b32_e32 v8, v9
	v_add_f32_e32 v8, v8, v9
	v_fmamk_f32 v8, v8, 0x3a800000, v17
	v_mul_f32_e32 v9, 0x4b800000, v8
	v_cmp_gt_f32_e64 s[4:5], s20, v8
	s_nop 1
	v_cndmask_b32_e64 v8, v8, v9, s[4:5]
	v_rsq_f32_e32 v8, v8
	s_nop 0
	v_mul_f32_e32 v9, 0x45800000, v8
	v_cndmask_b32_e64 v8, v8, v9, s[4:5]
	v_mul_f32_e32 v52, 0.5, v8
	v_pk_fma_f32 v[14:15], v[2:3], v[52:53], v[32:33] op_sel_hi:[1,0,1]
	v_pk_fma_f32 v[12:13], v[0:1], v[52:53], v[30:31] op_sel_hi:[1,0,1]
	v_pk_fma_f32 v[10:11], v[6:7], v[52:53], v[36:37] op_sel_hi:[1,0,1]
	v_pk_fma_f32 v[8:9], v[4:5], v[52:53], v[34:35] op_sel_hi:[1,0,1]
	v_pk_fma_f32 v[6:7], v[46:47], v[52:53], v[40:41] op_sel_hi:[1,0,1]
	v_pk_fma_f32 v[4:5], v[62:63], v[52:53], v[38:39] op_sel_hi:[1,0,1]
	v_pk_fma_f32 v[2:3], v[50:51], v[52:53], v[44:45] op_sel_hi:[1,0,1]
	v_pk_fma_f32 v[0:1], v[48:49], v[52:53], v[42:43] op_sel_hi:[1,0,1]
	global_load_dwordx4 v[40:43], v[22:23], off
	global_load_dwordx4 v[44:47], v[22:23], off offset:1024
	global_load_dwordx4 v[48:51], v[22:23], off offset:2048
	global_load_dwordx4 v[52:55], v[22:23], off offset:3072
	s_cbranch_vccnz .LBB0_2031
	global_store_dwordx4 v[28:29], v[12:15], off sc0 sc1
	s_nop 1
	v_lshl_add_u64 v[30:31], v[28:29], 0, s[14:15]
	global_store_dwordx4 v[30:31], v[8:11], off sc0 sc1
	s_nop 1
	v_lshl_add_u64 v[32:33], v[28:29], 0, s[16:17]
	global_store_dwordx4 v[32:33], v[4:7], off sc0 sc1
	s_nop 1
	v_lshl_add_u64 v[34:35], v[28:29], 0, s[18:19]
	global_store_dwordx4 v[34:35], v[0:3], off sc0 sc1
	s_nop 1
	s_branch .LBB0_2031

; DI unsigned pk2(float lo, float hi) { f32x2 v = {lo, hi}; bf16x2_t b = __builtin_convertvector(v, bf16x2_t); return __builtin_bit_cast(unsigned, b); }
; DI float bflo(unsigned u) { return __uint_as_float(u << 16); }
; DI float bfhi(unsigned u) { return __uint_as_float(u & 0xffff0000u); }
; DI void st16_wt(void* p, u32x4 v) { asm volatile("global_store_dwordx4 %0, %1, off sc0 sc1\n\ts_nop 1" :: "v"(p), "v"(v) : "memory"); }
; DI void row_phase(int wv, int mode, const float* X, const bf16_t* Y, const float* ga, float coef, const float* gb, float* Xout, bf16_t* A, int a_pad) {
;     ...
;     for (int r = gw; r < MTOK; r += NGW) {
;         f32x4 v[4];
; #pragma unroll
;         for (int j = 0; j < 4; ++j) v[j] = *(const f32x4*)(X + (size_t)r * DM + 4 * lane + 256 * j);
;         if (mode == 1) { f32x4 y[4]; float s = 0.f;
; #pragma unroll
;             for (int j = 0; j < 4; ++j) { const u32x2 yv = *(const u32x2*)(Y + (size_t)r * DM + 4 * lane + 256 * j); y[j] = (f32x4){bflo(yv.x), bfhi(yv.x), bflo(yv.y), bfhi(yv.y)}; s += y[j][0] * y[j][0] + y[j][1] * y[j][1] + y[j][2] * y[j][2] + y[j][3] * y[j][3]; }
;             const float rs = coef * rsqrtf(wave_sum(s) * (1.f / DM) + 1e-6f);
; #pragma unroll
;             for (int j = 0; j < 4; ++j) { const f32x4 gg = *(const f32x4*)(ga + 4 * lane + 256 * j); v[j] += y[j] * gg * rs; } }
;         if (Xout) {
; #pragma unroll
;             for (int j = 0; j < 4; ++j) st16_wt(Xout + (size_t)r * DM + 4 * lane + 256 * j, __builtin_bit_cast(u32x4, v[j])); }
;         if (gb) { float s = 0.f;
; #pragma unroll
;             for (int j = 0; j < 4; ++j) s += v[j][0] * v[j][0] + v[j][1] * v[j][1] + v[j][2] * v[j][2] + v[j][3] * v[j][3];
;             const float rs = rsqrtf(wave_sum(s) * (1.f / DM) + 1e-6f);
;             const size_t ar = a_pad ? (size_t)(r + (r >> 13) + 1) : (size_t)r;
; #pragma unroll
;             for (int j = 0; j < 4; ++j) { const f32x4 gg = *(const f32x4*)(gb + 4 * lane + 256 * j); const f32x4 o = v[j] * gg * rs;
;                 u32x2 w; w.x = pk2(o[0], o[1]); w.y = pk2(o[2], o[3]); *(u32x2*)(A + ar * DM + 4 * lane + 256 * j) = w; } }
.LBB0_2525:
	flat_load_dwordx2 v[46:47], v[24:25]
	flat_load_dwordx2 v[48:49], v[24:25] offset:512
	flat_load_dwordx2 v[50:51], v[24:25] offset:1024
	flat_load_dwordx2 v[52:53], v[24:25] offset:1536
	global_load_dwordx4 v[0:3], v[18:19], off nt
	global_load_dwordx4 v[4:7], v[18:19], off offset:1024 nt
	global_load_dwordx4 v[8:11], v[18:19], off offset:2048 nt
	global_load_dwordx4 v[12:15], v[18:19], off offset:3072 nt
	global_load_dwordx4 v[30:33], v[26:27], off nt
	global_load_dwordx4 v[34:37], v[26:27], off offset:1024 nt
	global_load_dwordx4 v[38:41], v[26:27], off offset:2048 nt
	global_load_dwordx4 v[42:45], v[26:27], off offset:3072 nt
	s_and_b64 vcc, exec, s[10:11]
	s_waitcnt vmcnt(0) lgkmcnt(0)
	v_and_b32_e32 v55, 0xffff0000, v46
	v_and_b32_e32 v57, 0xffff0000, v48
	v_lshlrev_b32_e32 v54, 16, v46
	v_lshlrev_b32_e32 v56, 16, v48
	v_and_b32_e32 v59, 0xffff0000, v50
	v_mul_f32_e32 v29, v55, v55
	v_mul_f32_e32 v64, v57, v57
	v_lshlrev_b32_e32 v46, 16, v47
	v_lshlrev_b32_e32 v48, 16, v49
	v_lshlrev_b32_e32 v58, 16, v50
	v_and_b32_e32 v61, 0xffff0000, v52
	v_mul_f32_e32 v65, v59, v59
	v_fmac_f32_e32 v29, v54, v54
	v_fmac_f32_e32 v64, v56, v56
	v_and_b32_e32 v47, 0xffff0000, v47
	v_and_b32_e32 v49, 0xffff0000, v49
	v_lshlrev_b32_e32 v50, 16, v51
	v_lshlrev_b32_e32 v60, 16, v52
	v_mul_f32_e32 v66, v61, v61
	v_fmac_f32_e32 v65, v58, v58
	v_fmac_f32_e32 v29, v46, v46
	v_fmac_f32_e32 v64, v48, v48
	v_and_b32_e32 v51, 0xffff0000, v51
	v_lshlrev_b32_e32 v52, 16, v53
	v_fmac_f32_e32 v66, v60, v60
	v_fmac_f32_e32 v65, v50, v50
	v_fmac_f32_e32 v29, v47, v47
	v_fmac_f32_e32 v64, v49, v49
	v_and_b32_e32 v53, 0xffff0000, v53
	v_pk_mul_f32 v[62:63], v[58:59], v[8:9]
	v_fmac_f32_e32 v66, v52, v52
	v_fmac_f32_e32 v65, v51, v51
	v_add_f32_e32 v8, v29, v64
	v_fmac_f32_e32 v66, v53, v53
	v_add_f32_e32 v8, v8, v65
	v_add_f32_e32 v8, v8, v66
	v_pk_mul_f32 v[0:1], v[54:55], v[0:1]
	v_pk_mul_f32 v[2:3], v[46:47], v[2:3]
	v_add_f32_dpp v8, v8, v8 quad_perm:[1,0,3,2] row_mask:0xf bank_mask:0xf bound_ctrl:1
	v_pk_mul_f32 v[4:5], v[56:57], v[4:5]
	v_pk_mul_f32 v[6:7], v[48:49], v[6:7]
	v_add_f32_dpp v8, v8, v8 quad_perm:[2,3,0,1] row_mask:0xf bank_mask:0xf bound_ctrl:1
	v_pk_mul_f32 v[46:47], v[50:51], v[10:11]
	v_pk_mul_f32 v[48:49], v[60:61], v[12:13]
	v_add_f32_dpp v8, v8, v8 row_half_mirror row_mask:0xf bank_mask:0xf bound_ctrl:1
	v_pk_mul_f32 v[50:51], v[52:53], v[14:15]
	s_nop 0
	v_add_f32_dpp v8, v8, v8 row_mirror row_mask:0xf bank_mask:0xf bound_ctrl:1
	v_mov_b32_e32 v9, v8
	s_nop 1
	v_permlane16_swap_b32_e32 v8, v9
	v_add_f32_e32 v8, v8, v9
	v_mov_b32_e32 v9, v8
	s_nop 1
	v_permlane32_swap_b32_e32 v8, v9
	v_add_f32_e32 v8, v8, v9
	v_fmamk_f32 v8, v8, 0x3a800000, v17
	v_mul_f32_e32 v9, 0x4b800000, v8
	v_cmp_gt_f32_e64 s[2:3], s22, v8
	s_nop 1
	v_cndmask_b32_e64 v8, v8, v9, s[2:3]
	v_rsq_f32_e32 v8, v8
	s_nop 0
	v_mul_f32_e32 v9, 0x45800000, v8
	v_cndmask_b32_e64 v8, v8, v9, s[2:3]
	v_mul_f32_e32 v52, 0.5, v8
	v_pk_fma_f32 v[14:15], v[2:3], v[52:53], v[32:33] op_sel_hi:[1,0,1]
	v_pk_fma_f32 v[12:13], v[0:1], v[52:53], v[30:31] op_sel_hi:[1,0,1]
	v_pk_fma_f32 v[10:11], v[6:7], v[52:53], v[36:37] op_sel_hi:[1,0,1]
	v_pk_fma_f32 v[8:9], v[4:5], v[52:53], v[34:35] op_sel_hi:[1,0,1]
	v_pk_fma_f32 v[6:7], v[46:47], v[52:53], v[40:41] op_sel_hi:[1,0,1]
	v_pk_fma_f32 v[4:5], v[62:63], v[52:53], v[38:39] op_sel_hi:[1,0,1]
	v_pk_fma_f32 v[2:3], v[50:51], v[52:53], v[44:45] op_sel_hi:[1,0,1]
	v_pk_fma_f32 v[0:1], v[48:49], v[52:53], v[42:43] op_sel_hi:[1,0,1]
	global_load_dwordx4 v[40:43], v[20:21], off
	global_load_dwordx4 v[44:47], v[20:21], off offset:1024
	global_load_dwordx4 v[48:51], v[20:21], off offset:2048
	global_load_dwordx4 v[52:55], v[20:21], off offset:3072
	s_cbranch_vccz .LBB0_2524
	global_store_dwordx4 v[26:27], v[12:15], off sc0 sc1
	s_nop 1
	v_lshl_add_u64 v[30:31], v[26:27], 0, s[16:17]
	global_store_dwordx4 v[30:31], v[8:11], off sc0 sc1
	s_nop 1
	v_lshl_add_u64 v[32:33], v[26:27], 0, s[18:19]
	global_store_dwordx4 v[32:33], v[4:7], off sc0 sc1
	s_nop 1
	v_lshl_add_u64 v[34:35], v[26:27], 0, s[20:21]
	global_store_dwordx4 v[34:35], v[0:3], off sc0 sc1
	s_nop 1
	s_branch .LBB0_2524

; DI unsigned pk2(float lo, float hi) { f32x2 v = {lo, hi}; bf16x2_t b = __builtin_convertvector(v, bf16x2_t); return __builtin_bit_cast(unsigned, b); }
; DI float bflo(unsigned u) { return __uint_as_float(u << 16); }
; DI float bfhi(unsigned u) { return __uint_as_float(u & 0xffff0000u); }
; DI void st16_wt(void* p, u32x4 v) { asm volatile("global_store_dwordx4 %0, %1, off sc0 sc1\n\ts_nop 1" :: "v"(p), "v"(v) : "memory"); }
; DI void row_phase(int wv, int mode, const float* X, const bf16_t* Y, const float* ga, float coef, const float* gb, float* Xout, bf16_t* A, int a_pad) {
;     ...
;     for (int r = gw; r < MTOK; r += NGW) {
;         f32x4 v[4];
; #pragma unroll
;         for (int j = 0; j < 4; ++j) v[j] = *(const f32x4*)(X + (size_t)r * DM + 4 * lane + 256 * j);
;         if (mode == 1) { f32x4 y[4]; float s = 0.f;
; #pragma unroll
;             for (int j = 0; j < 4; ++j) { const u32x2 yv = *(const u32x2*)(Y + (size_t)r * DM + 4 * lane + 256 * j); y[j] = (f32x4){bflo(yv.x), bfhi(yv.x), bflo(yv.y), bfhi(yv.y)}; s += y[j][0] * y[j][0] + y[j][1] * y[j][1] + y[j][2] * y[j][2] + y[j][3] * y[j][3]; }
;             const float rs = coef * rsqrtf(wave_sum(s) * (1.f / DM) + 1e-6f);
; #pragma unroll
;             for (int j = 0; j < 4; ++j) { const f32x4 gg = *(const f32x4*)(ga + 4 * lane + 256 * j); v[j] += y[j] * gg * rs; } }
;         if (Xout) {
; #pragma unroll
;             for (int j = 0; j < 4; ++j) st16_wt(Xout + (size_t)r * DM + 4 * lane + 256 * j, __builtin_bit_cast(u32x4, v[j])); }
;         if (gb) { float s = 0.f;
; #pragma unroll
;             for (int j = 0; j < 4; ++j) s += v[j][0] * v[j][0] + v[j][1] * v[j][1] + v[j][2] * v[j][2] + v[j][3] * v[j][3];
;             const float rs = rsqrtf(wave_sum(s) * (1.f / DM) + 1e-6f);
;             const size_t ar = a_pad ? (size_t)(r + (r >> 13) + 1) : (size_t)r;
; #pragma unroll
;             for (int j = 0; j < 4; ++j) { const f32x4 gg = *(const f32x4*)(gb + 4 * lane + 256 * j); const f32x4 o = v[j] * gg * rs;
;                 u32x2 w; w.x = pk2(o[0], o[1]); w.y = pk2(o[2], o[3]); *(u32x2*)(A + ar * DM + 4 * lane + 256 * j) = w; } }
.LBB0_3476:
	v_lshl_add_u64 v[0:1], v[26:27], 0, v[18:19]
	v_add_co_u32_e32 v46, vcc, 0x7000000, v0
	s_nop 1
	v_addc_co_u32_e32 v47, vcc, 0, v1, vcc
	flat_load_dwordx2 v[48:49], v[46:47]
	flat_load_dwordx2 v[50:51], v[46:47] offset:512
	flat_load_dwordx2 v[52:53], v[46:47] offset:1024
	flat_load_dwordx2 v[54:55], v[46:47] offset:1536
	global_load_dwordx4 v[0:3], v[20:21], off nt
	global_load_dwordx4 v[4:7], v[20:21], off offset:1024 nt
	global_load_dwordx4 v[8:11], v[20:21], off offset:2048 nt
	global_load_dwordx4 v[12:15], v[20:21], off offset:3072 nt
	global_load_dwordx4 v[30:33], v[28:29], off nt
	global_load_dwordx4 v[34:37], v[28:29], off offset:1024 nt
	global_load_dwordx4 v[38:41], v[28:29], off offset:2048 nt
	global_load_dwordx4 v[42:45], v[28:29], off offset:3072 nt
	s_and_b64 vcc, exec, s[0:1]
	s_waitcnt vmcnt(0) lgkmcnt(0)
	v_and_b32_e32 v47, 0xffff0000, v48
	v_and_b32_e32 v57, 0xffff0000, v50
	v_lshlrev_b32_e32 v46, 16, v48
	v_lshlrev_b32_e32 v56, 16, v50
	v_and_b32_e32 v59, 0xffff0000, v52
	v_mul_f32_e32 v64, v47, v47
	v_mul_f32_e32 v65, v57, v57
	v_lshlrev_b32_e32 v48, 16, v49
	v_lshlrev_b32_e32 v50, 16, v51
	v_lshlrev_b32_e32 v58, 16, v52
	v_and_b32_e32 v61, 0xffff0000, v54
	v_mul_f32_e32 v66, v59, v59
	v_fmac_f32_e32 v64, v46, v46
	v_fmac_f32_e32 v65, v56, v56
	v_and_b32_e32 v49, 0xffff0000, v49
	v_and_b32_e32 v51, 0xffff0000, v51
	v_lshlrev_b32_e32 v52, 16, v53
	v_lshlrev_b32_e32 v60, 16, v54
	v_mul_f32_e32 v67, v61, v61
	v_fmac_f32_e32 v66, v58, v58
	v_fmac_f32_e32 v64, v48, v48
	v_fmac_f32_e32 v65, v50, v50
	v_and_b32_e32 v53, 0xffff0000, v53
	v_lshlrev_b32_e32 v54, 16, v55
	v_fmac_f32_e32 v67, v60, v60
	v_fmac_f32_e32 v66, v52, v52
	v_fmac_f32_e32 v64, v49, v49
	v_fmac_f32_e32 v65, v51, v51
	v_and_b32_e32 v55, 0xffff0000, v55
	v_pk_mul_f32 v[62:63], v[58:59], v[8:9]
	v_fmac_f32_e32 v67, v54, v54
	v_fmac_f32_e32 v66, v53, v53
	v_add_f32_e32 v8, v64, v65
	v_fmac_f32_e32 v67, v55, v55
	v_add_f32_e32 v8, v8, v66
	v_add_f32_e32 v8, v8, v67
	v_pk_mul_f32 v[0:1], v[46:47], v[0:1]
	v_pk_mul_f32 v[2:3], v[48:49], v[2:3]
	v_add_f32_dpp v8, v8, v8 quad_perm:[1,0,3,2] row_mask:0xf bank_mask:0xf bound_ctrl:1
	v_pk_mul_f32 v[4:5], v[56:57], v[4:5]
	v_pk_mul_f32 v[6:7], v[50:51], v[6:7]
	v_add_f32_dpp v8, v8, v8 quad_perm:[2,3,0,1] row_mask:0xf bank_mask:0xf bound_ctrl:1
	v_pk_mul_f32 v[46:47], v[52:53], v[10:11]
	v_pk_mul_f32 v[48:49], v[60:61], v[12:13]
	v_add_f32_dpp v8, v8, v8 row_half_mirror row_mask:0xf bank_mask:0xf bound_ctrl:1
	v_pk_mul_f32 v[50:51], v[54:55], v[14:15]
	s_nop 0
	v_add_f32_dpp v8, v8, v8 row_mirror row_mask:0xf bank_mask:0xf bound_ctrl:1
	v_mov_b32_e32 v9, v8
	s_nop 1
	v_permlane16_swap_b32_e32 v8, v9
	v_add_f32_e32 v8, v8, v9
	v_mov_b32_e32 v9, v8
	s_nop 1
	v_permlane32_swap_b32_e32 v8, v9
	v_add_f32_e32 v8, v8, v9
	v_fmamk_f32 v8, v8, 0x3a800000, v17
	v_mul_f32_e32 v9, 0x4b800000, v8
	v_cmp_gt_f32_e64 s[2:3], s18, v8
	s_nop 1
	v_cndmask_b32_e64 v8, v8, v9, s[2:3]
	v_rsq_f32_e32 v8, v8
	s_nop 0
	v_mul_f32_e32 v9, 0x45800000, v8
	v_cndmask_b32_e64 v52, v8, v9, s[2:3]
	v_pk_fma_f32 v[14:15], v[2:3], v[52:53], v[32:33] op_sel_hi:[1,0,1]
	v_pk_fma_f32 v[12:13], v[0:1], v[52:53], v[30:31] op_sel_hi:[1,0,1]
	v_pk_fma_f32 v[10:11], v[6:7], v[52:53], v[36:37] op_sel_hi:[1,0,1]
	v_pk_fma_f32 v[8:9], v[4:5], v[52:53], v[34:35] op_sel_hi:[1,0,1]
	v_pk_fma_f32 v[6:7], v[46:47], v[52:53], v[40:41] op_sel_hi:[1,0,1]
	v_pk_fma_f32 v[4:5], v[62:63], v[52:53], v[38:39] op_sel_hi:[1,0,1]
	v_pk_fma_f32 v[2:3], v[50:51], v[52:53], v[44:45] op_sel_hi:[1,0,1]
	v_pk_fma_f32 v[0:1], v[48:49], v[52:53], v[42:43] op_sel_hi:[1,0,1]
	global_load_dwordx4 v[40:43], v[22:23], off
	global_load_dwordx4 v[44:47], v[22:23], off offset:1024
	global_load_dwordx4 v[48:51], v[22:23], off offset:2048
	global_load_dwordx4 v[52:55], v[22:23], off offset:3072
	s_cbranch_vccnz .LBB0_3475
	global_store_dwordx4 v[28:29], v[12:15], off sc0 sc1
	s_nop 1
	v_lshl_add_u64 v[30:31], v[28:29], 0, s[12:13]
	global_store_dwordx4 v[30:31], v[8:11], off sc0 sc1
	s_nop 1
	v_lshl_add_u64 v[32:33], v[28:29], 0, s[14:15]
	global_store_dwordx4 v[32:33], v[4:7], off sc0 sc1
	s_nop 1
	v_lshl_add_u64 v[34:35], v[28:29], 0, s[16:17]
	global_store_dwordx4 v[34:35], v[0:3], off sc0 sc1
	s_nop 1
	s_branch .LBB0_3475

; DI float bflo(unsigned u) { return __uint_as_float(u << 16); }
; DI float bfhi(unsigned u) { return __uint_as_float(u & 0xffff0000u); }
; DI void st16_wt(void* p, u32x4 v) { asm volatile("global_store_dwordx4 %0, %1, off sc0 sc1\n\ts_nop 1" :: "v"(p), "v"(v) : "memory"); }
; DI void row_phase(int wv, int mode, const float* X, const bf16_t* Y, const float* ga, float coef, const float* gb, float* Xout, bf16_t* A, int a_pad) {
;     ...
;     for (int r = gw; r < MTOK; r += NGW) {
;         f32x4 v[4];
; #pragma unroll
;         for (int j = 0; j < 4; ++j) v[j] = *(const f32x4*)(X + (size_t)r * DM + 4 * lane + 256 * j);
;         if (mode == 1) { f32x4 y[4]; float s = 0.f;
; #pragma unroll
;             for (int j = 0; j < 4; ++j) { const u32x2 yv = *(const u32x2*)(Y + (size_t)r * DM + 4 * lane + 256 * j); y[j] = (f32x4){bflo(yv.x), bfhi(yv.x), bflo(yv.y), bfhi(yv.y)}; s += y[j][0] * y[j][0] + y[j][1] * y[j][1] + y[j][2] * y[j][2] + y[j][3] * y[j][3]; }
;             const float rs = coef * rsqrtf(wave_sum(s) * (1.f / DM) + 1e-6f);
; #pragma unroll
;             for (int j = 0; j < 4; ++j) { const f32x4 gg = *(const f32x4*)(ga + 4 * lane + 256 * j); v[j] += y[j] * gg * rs; } }
;         if (Xout) {
; #pragma unroll
;             for (int j = 0; j < 4; ++j) st16_wt(Xout + (size_t)r * DM + 4 * lane + 256 * j, __builtin_bit_cast(u32x4, v[j])); }
.LBB0_3676:
	flat_load_dwordx2 v[10:11], v[4:5]
	flat_load_dwordx2 v[14:15], v[4:5] offset:512
	flat_load_dwordx2 v[18:19], v[4:5] offset:1024
	flat_load_dwordx2 v[22:23], v[4:5] offset:1536
	s_and_b64 vcc, exec, s[0:1]
	s_waitcnt vmcnt(0) lgkmcnt(0)
	v_and_b32_e32 v9, 0xffff0000, v10
	v_and_b32_e32 v13, 0xffff0000, v14
	v_lshlrev_b32_e32 v8, 16, v10
	v_lshlrev_b32_e32 v12, 16, v14
	v_and_b32_e32 v17, 0xffff0000, v18
	v_mul_f32_e32 v24, v9, v9
	v_mul_f32_e32 v25, v13, v13
	v_lshlrev_b32_e32 v10, 16, v11
	v_lshlrev_b32_e32 v14, 16, v15
	v_lshlrev_b32_e32 v16, 16, v18
	v_and_b32_e32 v21, 0xffff0000, v22
	v_mul_f32_e32 v26, v17, v17
	v_fmac_f32_e32 v24, v8, v8
	v_fmac_f32_e32 v25, v12, v12
	v_and_b32_e32 v11, 0xffff0000, v11
	v_and_b32_e32 v15, 0xffff0000, v15
	v_lshlrev_b32_e32 v18, 16, v19
	v_lshlrev_b32_e32 v20, 16, v22
	v_mul_f32_e32 v27, v21, v21
	v_fmac_f32_e32 v26, v16, v16
	v_fmac_f32_e32 v24, v10, v10
	v_fmac_f32_e32 v25, v14, v14
	v_and_b32_e32 v19, 0xffff0000, v19
	v_lshlrev_b32_e32 v22, 16, v23
	v_fmac_f32_e32 v27, v20, v20
	v_fmac_f32_e32 v26, v18, v18
	v_fmac_f32_e32 v24, v11, v11
	v_fmac_f32_e32 v25, v15, v15
	v_and_b32_e32 v23, 0xffff0000, v23
	v_fmac_f32_e32 v27, v22, v22
	v_fmac_f32_e32 v26, v19, v19
	v_add_f32_e32 v24, v24, v25
	v_fmac_f32_e32 v27, v23, v23
	v_add_f32_e32 v24, v24, v26
	v_add_f32_e32 v24, v24, v27
	s_nop 1
	v_add_f32_dpp v24, v24, v24 quad_perm:[1,0,3,2] row_mask:0xf bank_mask:0xf bound_ctrl:1
	s_nop 1
	v_add_f32_dpp v24, v24, v24 quad_perm:[2,3,0,1] row_mask:0xf bank_mask:0xf bound_ctrl:1
	s_nop 1
	v_add_f32_dpp v24, v24, v24 row_half_mirror row_mask:0xf bank_mask:0xf bound_ctrl:1
	s_nop 1
	v_add_f32_dpp v24, v24, v24 row_mirror row_mask:0xf bank_mask:0xf bound_ctrl:1
	v_mov_b32_e32 v25, v24
	s_nop 1
	v_permlane16_swap_b32_e32 v24, v25
	v_add_f32_e32 v24, v24, v25
	v_mov_b32_e32 v25, v24
	s_nop 1
	v_permlane32_swap_b32_e32 v24, v25
	s_cbranch_vccnz .LBB0_3675
	global_load_dwordx4 v[26:29], v[2:3], off offset:3072 nt
	global_load_dwordx4 v[30:33], v[2:3], off offset:2048 nt
	global_load_dwordx4 v[34:37], v[2:3], off offset:1024 nt
	global_load_dwordx4 v[38:41], v[2:3], off nt
	global_load_dwordx4 v[42:45], v[6:7], off offset:3072 nt
	global_load_dwordx4 v[46:49], v[6:7], off offset:2048 nt
	global_load_dwordx4 v[50:53], v[6:7], off offset:1024 nt
	global_load_dwordx4 v[54:57], v[6:7], off nt
	v_add_f32_e32 v24, v24, v25
	v_fmamk_f32 v24, v24, 0x3a800000, v1
	v_mul_f32_e32 v25, 0x4b800000, v24
	v_cmp_gt_f32_e32 vcc, s14, v24
	v_lshl_add_u64 v[60:61], v[6:7], 0, s[12:13]
	v_lshl_add_u64 v[58:59], v[6:7], 0, s[10:11]
	v_cndmask_b32_e32 v24, v24, v25, vcc
	v_rsq_f32_e32 v62, v24
	v_lshl_add_u64 v[24:25], v[6:7], 0, s[8:9]
	v_mul_f32_e32 v63, 0x45800000, v62
	v_cndmask_b32_e32 v62, v62, v63, vcc
	v_mul_f32_e32 v62, 0.5, v62
	s_waitcnt vmcnt(7)
	v_pk_mul_f32 v[22:23], v[22:23], v[28:29]
	v_pk_mul_f32 v[20:21], v[20:21], v[26:27]
	s_waitcnt vmcnt(6)
	v_pk_mul_f32 v[18:19], v[18:19], v[32:33]
	v_pk_mul_f32 v[16:17], v[16:17], v[30:31]
	s_waitcnt vmcnt(4)
	v_pk_mul_f32 v[30:31], v[10:11], v[40:41]
	v_pk_mul_f32 v[32:33], v[8:9], v[38:39]
	v_pk_mul_f32 v[26:27], v[14:15], v[36:37]
	v_pk_mul_f32 v[28:29], v[12:13], v[34:35]
	s_waitcnt vmcnt(3)
	v_pk_fma_f32 v[10:11], v[62:63], v[22:23], v[44:45] op_sel_hi:[0,1,1]
	v_pk_fma_f32 v[8:9], v[62:63], v[20:21], v[42:43] op_sel_hi:[0,1,1]
	s_waitcnt vmcnt(0)
	v_pk_fma_f32 v[22:23], v[62:63], v[30:31], v[56:57] op_sel_hi:[0,1,1]
	v_pk_fma_f32 v[20:21], v[62:63], v[32:33], v[54:55] op_sel_hi:[0,1,1]
	global_store_dwordx4 v[6:7], v[20:23], off sc0 sc1
	s_nop 1
	v_pk_fma_f32 v[14:15], v[62:63], v[18:19], v[48:49] op_sel_hi:[0,1,1]
	v_pk_fma_f32 v[12:13], v[62:63], v[16:17], v[46:47] op_sel_hi:[0,1,1]
	v_pk_fma_f32 v[18:19], v[62:63], v[26:27], v[52:53] op_sel_hi:[0,1,1]
	v_pk_fma_f32 v[16:17], v[62:63], v[28:29], v[50:51] op_sel_hi:[0,1,1]
	global_store_dwordx4 v[60:61], v[16:19], off sc0 sc1
	s_nop 1
	global_store_dwordx4 v[58:59], v[12:15], off sc0 sc1
	s_nop 1
	global_store_dwordx4 v[24:25], v[8:11], off sc0 sc1
	s_nop 1
	s_branch .LBB0_3675
